# gather: window of 2 experts in flight, packed f32 FMA replaced by scalar v_fmac pairs (same math)
# speedup vs baseline: 1.0317x; 1.0112x over previous
; #define P (*launderP(lp))
; __device__ __forceinline__ void phase_peer_gather(PREF P, int slab, int tbeg, int tend) {
;     ...
;     for (int half = 0; half < 2; ++half) {
;       const int ev = P.eidx[(size_t)t * 128 + half * 64 + lane];
;       const int gv = __float_as_int(P.gw[(size_t)t * 128 + half * 64 + lane]);
;       const int suv = __float_as_int(P.su[ev]);
;       const int svv = __float_as_int(P.sv[ev]);
; #pragma unroll 1
;       for (int e = 0; e < 64; e += 4) {
;         u32x4 ua[4][2], va[4][2];
;         float cg[4], csu[4], csv[4];
; #pragma unroll
;         for (int k = 0; k < 4; ++k) {
;           const int ix = __builtin_amdgcn_readlane(ev, e + k);
;           cg[k] = __int_as_float(__builtin_amdgcn_readlane(gv, e + k));
;           csu[k] = __int_as_float(__builtin_amdgcn_readlane(suv, e + k));
;           csv[k] = __int_as_float(__builtin_amdgcn_readlane(svv, e + k));
;           typedef const __attribute__((address_space(1))) u32x4* gvec_t;
;           gbytes_t up = U8 + (size_t)ix * 2048 + lane * 16;
;           gbytes_t vp = V8 + (size_t)ix * 2048 + lane * 16;
;           ua[k][0] = *(gvec_t)up; ua[k][1] = *(gvec_t)(up + 1024);
;           va[k][0] = *(gvec_t)vp; va[k][1] = *(gvec_t)(vp + 1024);
;         }
;         int id[4];
; #pragma unroll
;         for (int k = 0; k < 4; ++k) {
;           int d = 0;
;           d = __builtin_amdgcn_sdot4((int)ua[k][0].x, xq[0], d, false); d = __builtin_amdgcn_sdot4((int)ua[k][0].y, xq[1], d, false);
;           d = __builtin_amdgcn_sdot4((int)ua[k][0].z, xq[2], d, false); d = __builtin_amdgcn_sdot4((int)ua[k][0].w, xq[3], d, false);
;           d = __builtin_amdgcn_sdot4((int)ua[k][1].x, xq[4], d, false); d = __builtin_amdgcn_sdot4((int)ua[k][1].y, xq[5], d, false);
;           d = __builtin_amdgcn_sdot4((int)ua[k][1].z, xq[6], d, false); d = __builtin_amdgcn_sdot4((int)ua[k][1].w, xq[7], d, false);
;           id[k] = d;
;         }
; #pragma unroll
;         for (int k = 0; k < 4; ++k) id[k] = wsum_i(id[k]);
; #pragma unroll
;         for (int k = 0; k < 4; ++k) {
;           const float d = (float)id[k] * csu[k] * sh;
;           const float c = cg[k] * gelu_exact(d) * csv[k];
;           csum += c;
;           axpy_ub(acc + 0, c, va[k][0].x);  axpy_ub(acc + 4, c, va[k][0].y);
;           axpy_ub(acc + 8, c, va[k][0].z);  axpy_ub(acc + 12, c, va[k][0].w);
.LBB0_156:
	s_waitcnt lgkmcnt(0)
	v_lshlrev_b64 v[8:9], 2, v[100:101]
	v_readlane_b32 s68, v4, 0
	v_readlane_b32 s69, v5, 0
	v_lshl_add_u64 v[10:11], v[102:103], 0, v[8:9]
	v_lshl_add_u64 v[12:13], v[2:3], 0, v[8:9]
	global_load_dword v104, v[10:11], off
	global_load_dword v105, v[10:11], off offset:256
	global_load_dword v49, v[12:13], off
	global_load_dword v149, v[12:13], off offset:256
	v_readlane_b32 s70, v6, 0
	v_readlane_b32 s71, v7, 0
	v_readlane_b32 s62, v56, 0
	v_readlane_b32 s63, v57, 0
	v_readlane_b32 s64, v58, 0
	v_readlane_b32 s65, v59, 0
	v_mov_b32_e32 v186, 0
	s_mov_b32 s77, 0
	s_waitcnt vmcnt(2)
	v_lshlrev_b32_e32 v2, 2, v104
	v_lshlrev_b32_e32 v3, 2, v105
	v_mov_b32_e32 v174, v104
	s_mov_b32 s66, s62
	s_mov_b32 s67, s63
	global_load_dword v102, v2, s[68:69]
	global_load_dword v103, v3, s[68:69]
	global_load_dword v100, v2, s[70:71]
	global_load_dword v101, v3, s[70:71]
	v_readlane_b32 s74, v174, 0
	s_lshl_b32 s74, s74, 11
	s_add_u32 s72, s66, s74
	s_addc_u32 s73, s67, 0
	global_load_dwordx4 v[8:11], v54, s[72:73]
	global_load_dwordx4 v[12:15], v54, s[72:73] offset:1024
	v_readlane_b32 s74, v174, 1
	s_lshl_b32 s74, s74, 11
	s_add_u32 s72, s66, s74
	s_addc_u32 s73, s67, 0
	global_load_dwordx4 v[16:19], v54, s[72:73]
	global_load_dwordx4 v[20:23], v54, s[72:73] offset:1024
.Lpga_half:
	s_mov_b32 s75, 0
.Lpga_p1:
	s_cmp_eq_u32 s75, 62
	s_cselect_b32 s66, s64, s62
	s_cselect_b32 s67, s65, s63
	s_add_i32 s76, s75, 2
	s_and_b32 s76, s76, 63
	s_waitcnt vmcnt(2)
	v_mov_b32_e32 v221, 0
	v_dot4c_i32_i8_e32 v221, v8, v63
	v_dot4c_i32_i8_e32 v221, v9, v65
	v_dot4c_i32_i8_e32 v221, v10, v67
	v_dot4c_i32_i8_e32 v221, v11, v144
	v_dot4c_i32_i8_e32 v221, v12, v145
	v_dot4c_i32_i8_e32 v221, v13, v146
	v_dot4c_i32_i8_e32 v221, v14, v147
	v_dot4c_i32_i8_e32 v221, v15, v148
	v_readlane_b32 s74, v174, s76
	s_lshl_b32 s74, s74, 11
	s_add_u32 s72, s66, s74
	s_addc_u32 s73, s67, 0
	global_load_dwordx4 v[8:11], v54, s[72:73]
	global_load_dwordx4 v[12:15], v54, s[72:73] offset:1024
	s_waitcnt vmcnt(2)
	v_mov_b32_e32 v222, 0
	v_dot4c_i32_i8_e32 v222, v16, v63
	v_dot4c_i32_i8_e32 v222, v17, v65
	v_dot4c_i32_i8_e32 v222, v18, v67
	v_dot4c_i32_i8_e32 v222, v19, v144
	v_dot4c_i32_i8_e32 v222, v20, v145
	v_dot4c_i32_i8_e32 v222, v21, v146
	v_dot4c_i32_i8_e32 v222, v22, v147
	v_dot4c_i32_i8_e32 v222, v23, v148
	s_add_i32 s78, s76, 1
	v_readlane_b32 s74, v174, s78
	s_lshl_b32 s74, s74, 11
	s_add_u32 s72, s66, s74
	s_addc_u32 s73, s67, 0
	global_load_dwordx4 v[16:19], v54, s[72:73]
	global_load_dwordx4 v[20:23], v54, s[72:73] offset:1024
	v_add_u32_dpp v221, v221, v221 quad_perm:[1,0,3,2] row_mask:0xf bank_mask:0xf
	v_add_u32_dpp v222, v222, v222 quad_perm:[1,0,3,2] row_mask:0xf bank_mask:0xf
	s_nop 0
	v_add_u32_dpp v221, v221, v221 quad_perm:[2,3,0,1] row_mask:0xf bank_mask:0xf
	v_add_u32_dpp v222, v222, v222 quad_perm:[2,3,0,1] row_mask:0xf bank_mask:0xf
	s_nop 0
	v_add_u32_dpp v221, v221, v221 row_half_mirror row_mask:0xf bank_mask:0xf
	v_add_u32_dpp v222, v222, v222 row_half_mirror row_mask:0xf bank_mask:0xf
	s_nop 0
	v_add_u32_dpp v221, v221, v221 row_mirror row_mask:0xf bank_mask:0xf
	v_add_u32_dpp v222, v222, v222 row_mirror row_mask:0xf bank_mask:0xf
	s_nop 0
	v_add_u32_dpp v221, v221, v221 row_bcast:15 row_mask:0xa bank_mask:0xf
	v_add_u32_dpp v222, v222, v222 row_bcast:15 row_mask:0xa bank_mask:0xf
	s_nop 0
	v_add_u32_dpp v221, v221, v221 row_bcast:31 row_mask:0xc bank_mask:0xf
	v_add_u32_dpp v222, v222, v222 row_bcast:31 row_mask:0xc bank_mask:0xf
	s_nop 0
	v_readlane_b32 s80, v221, 63
	v_readlane_b32 s82, v222, 63
	s_add_i32 m0, s75, 0
	s_nop 0
	v_writelane_b32 v175, s80, m0
	s_add_i32 m0, s75, 1
	s_nop 0
	v_writelane_b32 v175, s82, m0
	s_add_i32 s75, s75, 2
	s_cmp_lt_u32 s75, 64
	s_cbranch_scc1 .Lpga_p1
	v_cvt_f32_i32_e32 v2, v175
	v_mul_f32_e32 v2, v102, v2
	v_mul_f32_e32 v3, v61, v2
	v_mul_f32_e32 v4, 0x3f3504f3, v3
	v_fma_f32 v5, |v4|, s21, v204
	v_fma_f32 v5, |v4|, v5, s7
	v_fma_f32 v5, |v4|, v5, s3
	v_fma_f32 v5, |v4|, v5, s2
	v_fma_f32 v5, |v4|, v5, s34
	v_fma_f32 v5, |v4|, v5, s35
	v_fma_f32 v5, |v4|, v5, |v4|
	v_mul_f32_e32 v6, 0xbfb8aa3b, v5
	v_fma_f32 v7, v5, s22, -v6
	v_rndne_f32_e32 v187, v6
	v_fmac_f32_e32 v7, 0xb2a5705f, v5
	v_sub_f32_e32 v6, v6, v187
	v_add_f32_e32 v6, v6, v7
	v_cvt_i32_f32_e32 v7, v187
	v_exp_f32_e32 v6, v6
	v_cmp_nlt_f32_e32 vcc, s23, v5
	v_ldexp_f32 v6, v6, v7
	s_nop 0
	v_cndmask_b32_e32 v6, 0, v6, vcc
	v_cmp_ngt_f32_e32 vcc, s20, v5
	s_nop 1
	v_cndmask_b32_e32 v5, v205, v6, vcc
	v_sub_f32_e32 v5, 1.0, v5
	v_mul_f32_e32 v6, v4, v4
	v_fmamk_f32 v7, v6, 0xba1345e1, v190
	v_fmaak_f32 v7, v6, v7, 0xbcdac9b8
	v_fmaak_f32 v7, v6, v7, 0x3de703be
	v_fmaak_f32 v7, v6, v7, 0xbec09330
	v_fmaak_f32 v6, v6, v7, 0x3e0375d0
	v_fma_f32 v6, |v4|, v6, |v4|
	v_cmp_nlt_f32_e64 s[96:97], |v4|, 1.0
	s_nop 1
	v_cndmask_b32_e64 v5, v6, v5, s[96:97]
	v_bfi_b32 v4, s8, v5, v4
	v_mul_f32_e32 v3, 0.5, v3
	v_add_f32_e32 v4, 1.0, v4
	v_mul_f32_e32 v3, v3, v4
	v_mul_f32_e32 v3, v49, v3
	v_mul_f32_e32 v183, v100, v3
	v_fmac_f32_e32 v186, v100, v3
	s_mov_b32 s75, 0
	s_mov_b32 s66, s64
	s_mov_b32 s67, s65
.Lpga_p2:
	v_readlane_b32 s80, v183, s75
	s_add_i32 s78, s75, 1
	v_readlane_b32 s82, v183, s78
	s_add_i32 s76, s75, 2
	s_and_b32 s76, s76, 63
	s_cmp_eq_u32 s75, 62
	s_cbranch_scc0 .Lpga_p2body
	s_cmp_eq_u32 s77, 1
	s_cbranch_scc1 .Lpga_drain
	v_mov_b32_e32 v174, v105
	s_mov_b32 s66, s62
	s_mov_b32 s67, s63
; DEV float gelu_exact(float x) { return 0.5f * x * (1.f + erff(x * 0.70710678118654752f)); }
; __device__ __forceinline__ void phase_peer_gather(PREF P, int slab, int tbeg, int tend) {
;     ...
;         for (int k = 0; k < 4; ++k) {
;           const float d = (float)id[k] * csu[k] * sh;
;           const float c = cg[k] * gelu_exact(d) * csv[k];
;           csum += c;
;           axpy_ub(acc + 0, c, va[k][0].x);  axpy_ub(acc + 4, c, va[k][0].y);
;           axpy_ub(acc + 8, c, va[k][0].z);  axpy_ub(acc + 12, c, va[k][0].w);
;           axpy_ub(acc + 16, c, va[k][1].x); axpy_ub(acc + 20, c, va[k][1].y);
;           axpy_ub(acc + 24, c, va[k][1].z); axpy_ub(acc + 28, c, va[k][1].w);
;         }
.Lpga_p2body:
	s_waitcnt vmcnt(2)
	v_cvt_f32_ubyte0_e32 v230, v8
	v_cvt_f32_ubyte1_e32 v231, v8
	v_cvt_f32_ubyte2_e32 v232, v8
	v_cvt_f32_ubyte3_e32 v233, v8
	v_fmac_f32_e32 v134, s80, v230
	v_fmac_f32_e32 v135, s80, v231
	v_fmac_f32_e32 v132, s80, v232
	v_fmac_f32_e32 v133, s80, v233
	v_cvt_f32_ubyte0_e32 v234, v9
	v_cvt_f32_ubyte1_e32 v235, v9
	v_cvt_f32_ubyte2_e32 v236, v9
	v_cvt_f32_ubyte3_e32 v237, v9
	v_fmac_f32_e32 v130, s80, v234
	v_fmac_f32_e32 v131, s80, v235
	v_fmac_f32_e32 v128, s80, v236
	v_fmac_f32_e32 v129, s80, v237
	v_cvt_f32_ubyte0_e32 v238, v10
	v_cvt_f32_ubyte1_e32 v239, v10
	v_cvt_f32_ubyte2_e32 v240, v10
	v_cvt_f32_ubyte3_e32 v241, v10
	v_fmac_f32_e32 v126, s80, v238
	v_fmac_f32_e32 v127, s80, v239
	v_fmac_f32_e32 v124, s80, v240
	v_fmac_f32_e32 v125, s80, v241
	v_cvt_f32_ubyte0_e32 v242, v11
	v_cvt_f32_ubyte1_e32 v243, v11
	v_cvt_f32_ubyte2_e32 v244, v11
	v_cvt_f32_ubyte3_e32 v245, v11
	v_fmac_f32_e32 v122, s80, v242
	v_fmac_f32_e32 v123, s80, v243
	v_fmac_f32_e32 v120, s80, v244
	v_fmac_f32_e32 v121, s80, v245
	v_cvt_f32_ubyte0_e32 v230, v12
	v_cvt_f32_ubyte1_e32 v231, v12
	v_cvt_f32_ubyte2_e32 v232, v12
	v_cvt_f32_ubyte3_e32 v233, v12
	v_fmac_f32_e32 v118, s80, v230
	v_fmac_f32_e32 v119, s80, v231
	v_fmac_f32_e32 v116, s80, v232
	v_fmac_f32_e32 v117, s80, v233
	v_cvt_f32_ubyte0_e32 v234, v13
	v_cvt_f32_ubyte1_e32 v235, v13
	v_cvt_f32_ubyte2_e32 v236, v13
	v_cvt_f32_ubyte3_e32 v237, v13
	v_fmac_f32_e32 v114, s80, v234
	v_fmac_f32_e32 v115, s80, v235
	v_fmac_f32_e32 v112, s80, v236
	v_fmac_f32_e32 v113, s80, v237
	v_cvt_f32_ubyte0_e32 v238, v14
	v_cvt_f32_ubyte1_e32 v239, v14
	v_cvt_f32_ubyte2_e32 v240, v14
	v_cvt_f32_ubyte3_e32 v241, v14
	v_fmac_f32_e32 v110, s80, v238
	v_fmac_f32_e32 v111, s80, v239
	v_fmac_f32_e32 v108, s80, v240
	v_fmac_f32_e32 v109, s80, v241
	v_cvt_f32_ubyte0_e32 v242, v15
	v_cvt_f32_ubyte1_e32 v243, v15
	v_cvt_f32_ubyte2_e32 v244, v15
	v_cvt_f32_ubyte3_e32 v245, v15
	v_fmac_f32_e32 v106, s80, v242
	v_fmac_f32_e32 v107, s80, v243
	v_fmac_f32_e32 v136, s80, v244
	v_fmac_f32_e32 v137, s80, v245
	v_readlane_b32 s74, v174, s76
	s_lshl_b32 s74, s74, 11
	s_add_u32 s72, s66, s74
	s_addc_u32 s73, s67, 0
	global_load_dwordx4 v[8:11], v54, s[72:73]
	global_load_dwordx4 v[12:15], v54, s[72:73] offset:1024
	s_waitcnt vmcnt(2)
	v_cvt_f32_ubyte0_e32 v230, v16
	v_cvt_f32_ubyte1_e32 v231, v16
	v_cvt_f32_ubyte2_e32 v232, v16
	v_cvt_f32_ubyte3_e32 v233, v16
	v_fmac_f32_e32 v134, s82, v230
	v_fmac_f32_e32 v135, s82, v231
	v_fmac_f32_e32 v132, s82, v232
	v_fmac_f32_e32 v133, s82, v233
	v_cvt_f32_ubyte0_e32 v234, v17
	v_cvt_f32_ubyte1_e32 v235, v17
	v_cvt_f32_ubyte2_e32 v236, v17
	v_cvt_f32_ubyte3_e32 v237, v17
	v_fmac_f32_e32 v130, s82, v234
	v_fmac_f32_e32 v131, s82, v235
	v_fmac_f32_e32 v128, s82, v236
	v_fmac_f32_e32 v129, s82, v237
	v_cvt_f32_ubyte0_e32 v238, v18
	v_cvt_f32_ubyte1_e32 v239, v18
	v_cvt_f32_ubyte2_e32 v240, v18
	v_cvt_f32_ubyte3_e32 v241, v18
	v_fmac_f32_e32 v126, s82, v238
	v_fmac_f32_e32 v127, s82, v239
	v_fmac_f32_e32 v124, s82, v240
	v_fmac_f32_e32 v125, s82, v241
	v_cvt_f32_ubyte0_e32 v242, v19
	v_cvt_f32_ubyte1_e32 v243, v19
	v_cvt_f32_ubyte2_e32 v244, v19
	v_cvt_f32_ubyte3_e32 v245, v19
	v_fmac_f32_e32 v122, s82, v242
	v_fmac_f32_e32 v123, s82, v243
	v_fmac_f32_e32 v120, s82, v244
	v_fmac_f32_e32 v121, s82, v245
	v_cvt_f32_ubyte0_e32 v230, v20
	v_cvt_f32_ubyte1_e32 v231, v20
	v_cvt_f32_ubyte2_e32 v232, v20
	v_cvt_f32_ubyte3_e32 v233, v20
	v_fmac_f32_e32 v118, s82, v230
	v_fmac_f32_e32 v119, s82, v231
	v_fmac_f32_e32 v116, s82, v232
	v_fmac_f32_e32 v117, s82, v233
	v_cvt_f32_ubyte0_e32 v234, v21
	v_cvt_f32_ubyte1_e32 v235, v21
	v_cvt_f32_ubyte2_e32 v236, v21
	v_cvt_f32_ubyte3_e32 v237, v21
	v_fmac_f32_e32 v114, s82, v234
	v_fmac_f32_e32 v115, s82, v235
	v_fmac_f32_e32 v112, s82, v236
	v_fmac_f32_e32 v113, s82, v237
	v_cvt_f32_ubyte0_e32 v238, v22
	v_cvt_f32_ubyte1_e32 v239, v22
	v_cvt_f32_ubyte2_e32 v240, v22
	v_cvt_f32_ubyte3_e32 v241, v22
	v_fmac_f32_e32 v110, s82, v238
	v_fmac_f32_e32 v111, s82, v239
	v_fmac_f32_e32 v108, s82, v240
	v_fmac_f32_e32 v109, s82, v241
	v_cvt_f32_ubyte0_e32 v242, v23
	v_cvt_f32_ubyte1_e32 v243, v23
	v_cvt_f32_ubyte2_e32 v244, v23
	v_cvt_f32_ubyte3_e32 v245, v23
	v_fmac_f32_e32 v106, s82, v242
	v_fmac_f32_e32 v107, s82, v243
	v_fmac_f32_e32 v136, s82, v244
	v_fmac_f32_e32 v137, s82, v245
	s_add_i32 s78, s76, 1
	v_readlane_b32 s74, v174, s78
	s_lshl_b32 s74, s74, 11
	s_add_u32 s72, s66, s74
	s_addc_u32 s73, s67, 0
	global_load_dwordx4 v[16:19], v54, s[72:73]
	global_load_dwordx4 v[20:23], v54, s[72:73] offset:1024
	s_add_i32 s75, s75, 2
	s_cmp_lt_u32 s75, 64
	s_cbranch_scc1 .Lpga_p2
	v_mov_b32_e32 v49, v149
	v_mov_b32_e32 v102, v103
	v_mov_b32_e32 v100, v101
	s_mov_b32 s77, 1
	s_branch .Lpga_half
; DEV float gelu_exact(float x) { return 0.5f * x * (1.f + erff(x * 0.70710678118654752f)); }
; __device__ __forceinline__ void phase_peer_gather(PREF P, int slab, int tbeg, int tend) {
;     ...
;         for (int k = 0; k < 4; ++k) {
;           const float d = (float)id[k] * csu[k] * sh;
;           const float c = cg[k] * gelu_exact(d) * csv[k];
;           csum += c;
;           axpy_ub(acc + 0, c, va[k][0].x);  axpy_ub(acc + 4, c, va[k][0].y);
;           axpy_ub(acc + 8, c, va[k][0].z);  axpy_ub(acc + 12, c, va[k][0].w);
;           axpy_ub(acc + 16, c, va[k][1].x); axpy_ub(acc + 20, c, va[k][1].y);
;           axpy_ub(acc + 24, c, va[k][1].z); axpy_ub(acc + 28, c, va[k][1].w);
;         }
;       }
;     }
;     {
;       const float corr = 128.f * csum;
.Lpga_drain:
	s_waitcnt vmcnt(2)
	v_cvt_f32_ubyte0_e32 v230, v8
	v_cvt_f32_ubyte1_e32 v231, v8
	v_cvt_f32_ubyte2_e32 v232, v8
	v_cvt_f32_ubyte3_e32 v233, v8
	v_fmac_f32_e32 v134, s80, v230
	v_fmac_f32_e32 v135, s80, v231
	v_fmac_f32_e32 v132, s80, v232
	v_fmac_f32_e32 v133, s80, v233
	v_cvt_f32_ubyte0_e32 v234, v9
	v_cvt_f32_ubyte1_e32 v235, v9
	v_cvt_f32_ubyte2_e32 v236, v9
	v_cvt_f32_ubyte3_e32 v237, v9
	v_fmac_f32_e32 v130, s80, v234
	v_fmac_f32_e32 v131, s80, v235
	v_fmac_f32_e32 v128, s80, v236
	v_fmac_f32_e32 v129, s80, v237
	v_cvt_f32_ubyte0_e32 v238, v10
	v_cvt_f32_ubyte1_e32 v239, v10
	v_cvt_f32_ubyte2_e32 v240, v10
	v_cvt_f32_ubyte3_e32 v241, v10
	v_fmac_f32_e32 v126, s80, v238
	v_fmac_f32_e32 v127, s80, v239
	v_fmac_f32_e32 v124, s80, v240
	v_fmac_f32_e32 v125, s80, v241
	v_cvt_f32_ubyte0_e32 v242, v11
	v_cvt_f32_ubyte1_e32 v243, v11
	v_cvt_f32_ubyte2_e32 v244, v11
	v_cvt_f32_ubyte3_e32 v245, v11
	v_fmac_f32_e32 v122, s80, v242
	v_fmac_f32_e32 v123, s80, v243
	v_fmac_f32_e32 v120, s80, v244
	v_fmac_f32_e32 v121, s80, v245
	v_cvt_f32_ubyte0_e32 v230, v12
	v_cvt_f32_ubyte1_e32 v231, v12
	v_cvt_f32_ubyte2_e32 v232, v12
	v_cvt_f32_ubyte3_e32 v233, v12
	v_fmac_f32_e32 v118, s80, v230
	v_fmac_f32_e32 v119, s80, v231
	v_fmac_f32_e32 v116, s80, v232
	v_fmac_f32_e32 v117, s80, v233
	v_cvt_f32_ubyte0_e32 v234, v13
	v_cvt_f32_ubyte1_e32 v235, v13
	v_cvt_f32_ubyte2_e32 v236, v13
	v_cvt_f32_ubyte3_e32 v237, v13
	v_fmac_f32_e32 v114, s80, v234
	v_fmac_f32_e32 v115, s80, v235
	v_fmac_f32_e32 v112, s80, v236
	v_fmac_f32_e32 v113, s80, v237
	v_cvt_f32_ubyte0_e32 v238, v14
	v_cvt_f32_ubyte1_e32 v239, v14
	v_cvt_f32_ubyte2_e32 v240, v14
	v_cvt_f32_ubyte3_e32 v241, v14
	v_fmac_f32_e32 v110, s80, v238
	v_fmac_f32_e32 v111, s80, v239
	v_fmac_f32_e32 v108, s80, v240
	v_fmac_f32_e32 v109, s80, v241
	v_cvt_f32_ubyte0_e32 v242, v15
	v_cvt_f32_ubyte1_e32 v243, v15
	v_cvt_f32_ubyte2_e32 v244, v15
	v_cvt_f32_ubyte3_e32 v245, v15
	v_fmac_f32_e32 v106, s80, v242
	v_fmac_f32_e32 v107, s80, v243
	v_fmac_f32_e32 v136, s80, v244
	v_fmac_f32_e32 v137, s80, v245
	s_waitcnt vmcnt(0)
	v_cvt_f32_ubyte0_e32 v230, v16
	v_cvt_f32_ubyte1_e32 v231, v16
	v_cvt_f32_ubyte2_e32 v232, v16
	v_cvt_f32_ubyte3_e32 v233, v16
	v_fmac_f32_e32 v134, s82, v230
	v_fmac_f32_e32 v135, s82, v231
	v_fmac_f32_e32 v132, s82, v232
	v_fmac_f32_e32 v133, s82, v233
	v_cvt_f32_ubyte0_e32 v234, v17
	v_cvt_f32_ubyte1_e32 v235, v17
	v_cvt_f32_ubyte2_e32 v236, v17
	v_cvt_f32_ubyte3_e32 v237, v17
	v_fmac_f32_e32 v130, s82, v234
	v_fmac_f32_e32 v131, s82, v235
	v_fmac_f32_e32 v128, s82, v236
	v_fmac_f32_e32 v129, s82, v237
	v_cvt_f32_ubyte0_e32 v238, v18
	v_cvt_f32_ubyte1_e32 v239, v18
	v_cvt_f32_ubyte2_e32 v240, v18
	v_cvt_f32_ubyte3_e32 v241, v18
	v_fmac_f32_e32 v126, s82, v238
	v_fmac_f32_e32 v127, s82, v239
	v_fmac_f32_e32 v124, s82, v240
	v_fmac_f32_e32 v125, s82, v241
	v_cvt_f32_ubyte0_e32 v242, v19
	v_cvt_f32_ubyte1_e32 v243, v19
	v_cvt_f32_ubyte2_e32 v244, v19
	v_cvt_f32_ubyte3_e32 v245, v19
	v_fmac_f32_e32 v122, s82, v242
	v_fmac_f32_e32 v123, s82, v243
	v_fmac_f32_e32 v120, s82, v244
	v_fmac_f32_e32 v121, s82, v245
	v_cvt_f32_ubyte0_e32 v230, v20
	v_cvt_f32_ubyte1_e32 v231, v20
	v_cvt_f32_ubyte2_e32 v232, v20
	v_cvt_f32_ubyte3_e32 v233, v20
	v_fmac_f32_e32 v118, s82, v230
	v_fmac_f32_e32 v119, s82, v231
	v_fmac_f32_e32 v116, s82, v232
	v_fmac_f32_e32 v117, s82, v233
	v_cvt_f32_ubyte0_e32 v234, v21
	v_cvt_f32_ubyte1_e32 v235, v21
	v_cvt_f32_ubyte2_e32 v236, v21
	v_cvt_f32_ubyte3_e32 v237, v21
	v_fmac_f32_e32 v114, s82, v234
	v_fmac_f32_e32 v115, s82, v235
	v_fmac_f32_e32 v112, s82, v236
	v_fmac_f32_e32 v113, s82, v237
	v_cvt_f32_ubyte0_e32 v238, v22
	v_cvt_f32_ubyte1_e32 v239, v22
	v_cvt_f32_ubyte2_e32 v240, v22
	v_cvt_f32_ubyte3_e32 v241, v22
	v_fmac_f32_e32 v110, s82, v238
	v_fmac_f32_e32 v111, s82, v239
	v_fmac_f32_e32 v108, s82, v240
	v_fmac_f32_e32 v109, s82, v241
	v_cvt_f32_ubyte0_e32 v242, v23
	v_cvt_f32_ubyte1_e32 v243, v23
	v_cvt_f32_ubyte2_e32 v244, v23
	v_cvt_f32_ubyte3_e32 v245, v23
	v_fmac_f32_e32 v106, s82, v242
	v_fmac_f32_e32 v107, s82, v243
	v_fmac_f32_e32 v136, s82, v244
	v_fmac_f32_e32 v137, s82, v245
	s_nop 1
	v_add_f32_dpp v186, v186, v186 quad_perm:[1,0,3,2] row_mask:0xf bank_mask:0xf
	s_nop 1
	v_add_f32_dpp v186, v186, v186 quad_perm:[2,3,0,1] row_mask:0xf bank_mask:0xf
	s_nop 1
	v_add_f32_dpp v186, v186, v186 row_half_mirror row_mask:0xf bank_mask:0xf
	s_nop 1
	v_add_f32_dpp v186, v186, v186 row_mirror row_mask:0xf bank_mask:0xf
	s_nop 1
	v_add_f32_dpp v186, v186, v186 row_bcast:15 row_mask:0xa bank_mask:0xf
	s_nop 1
	v_add_f32_dpp v186, v186, v186 row_bcast:31 row_mask:0xc bank_mask:0xf
	s_nop 1
	v_readlane_b32 s80, v186, 63
	s_mov_b64 s[42:43], 64
	s_mov_b64 s[40:41], 0
	s_nop 1
	v_mov_b32_e32 v55, s80
	s_branch .LBB0_153

; #define P (*launderP(lp))
; __device__ __forceinline__ void phase_peer_gather(PREF P, int slab, int tbeg, int tend) {
;     ...
;     for (int half = 0; half < 2; ++half) {
;       const int ev = P.eidx[(size_t)t * 128 + half * 64 + lane];
;       const int gv = __float_as_int(P.gw[(size_t)t * 128 + half * 64 + lane]);
;       const int suv = __float_as_int(P.su[ev]);
;       const int svv = __float_as_int(P.sv[ev]);
; #pragma unroll 1
;       for (int e = 0; e < 64; e += 4) {
;         u32x4 ua[4][2], va[4][2];
;         float cg[4], csu[4], csv[4];
; #pragma unroll
;         for (int k = 0; k < 4; ++k) {
;           const int ix = __builtin_amdgcn_readlane(ev, e + k);
;           cg[k] = __int_as_float(__builtin_amdgcn_readlane(gv, e + k));
;           csu[k] = __int_as_float(__builtin_amdgcn_readlane(suv, e + k));
;           csv[k] = __int_as_float(__builtin_amdgcn_readlane(svv, e + k));
;           typedef const __attribute__((address_space(1))) u32x4* gvec_t;
;           gbytes_t up = U8 + (size_t)ix * 2048 + lane * 16;
;           gbytes_t vp = V8 + (size_t)ix * 2048 + lane * 16;
;           ua[k][0] = *(gvec_t)up; ua[k][1] = *(gvec_t)(up + 1024);
;           va[k][0] = *(gvec_t)vp; va[k][1] = *(gvec_t)(vp + 1024);
;         }
.LBB0_695:
	s_waitcnt lgkmcnt(0)
	v_lshlrev_b64 v[8:9], 2, v[100:101]
	v_readlane_b32 s68, v4, 0
	v_readlane_b32 s69, v5, 0
	v_lshl_add_u64 v[10:11], v[102:103], 0, v[8:9]
	v_lshl_add_u64 v[12:13], v[2:3], 0, v[8:9]
	global_load_dword v104, v[10:11], off
	global_load_dword v105, v[10:11], off offset:256
	global_load_dword v49, v[12:13], off
	global_load_dword v149, v[12:13], off offset:256
	v_readlane_b32 s70, v6, 0
	v_readlane_b32 s71, v7, 0
	v_readlane_b32 s62, v56, 0
	v_readlane_b32 s63, v57, 0
	v_readlane_b32 s64, v58, 0
	v_readlane_b32 s65, v59, 0
	v_mov_b32_e32 v186, 0
	s_mov_b32 s77, 0
	s_waitcnt vmcnt(2)
	v_lshlrev_b32_e32 v2, 2, v104
	v_lshlrev_b32_e32 v3, 2, v105
	v_mov_b32_e32 v174, v104
	s_mov_b32 s66, s62
	s_mov_b32 s67, s63
	global_load_dword v102, v2, s[68:69]
	global_load_dword v103, v3, s[68:69]
	global_load_dword v100, v2, s[70:71]
	global_load_dword v101, v3, s[70:71]
	v_readlane_b32 s74, v174, 0
	s_lshl_b32 s74, s74, 11
	s_add_u32 s72, s66, s74
	s_addc_u32 s73, s67, 0
	global_load_dwordx4 v[8:11], v54, s[72:73]
	global_load_dwordx4 v[12:15], v54, s[72:73] offset:1024
	v_readlane_b32 s74, v174, 1
	s_lshl_b32 s74, s74, 11
	s_add_u32 s72, s66, s74
	s_addc_u32 s73, s67, 0
	global_load_dwordx4 v[16:19], v54, s[72:73]
	global_load_dwordx4 v[20:23], v54, s[72:73] offset:1024
.Lpgb_half:
	s_mov_b32 s75, 0
